# resched-6-gemm-loops-interleave-loads-writes
# speedup vs baseline: 1.0663x; 1.0663x over previous
.LBB0_122:
.Lrs1_top:
	s_cmp_eq_u32 s6, 0
	ds_read_b128 v[52:55], v116 offset:0
	ds_read_b128 v[48:51], v116 offset:0x800
	ds_read_b128 v[44:47], v116 offset:0x1000
	ds_read_b128 v[96:99], v114 offset:0
	ds_read_b128 v[92:95], v114 offset:0x800
	ds_read_b128 v[88:91], v114 offset:0x1000
	ds_read_b128 v[56:59], v114 offset:0x1800
	s_cbranch_scc1 .Lrs1_skip
	v_mfma_f32_32x32x16_bf16 a[32:47], v[198:201], v[40:43], a[32:47]
	v_mfma_f32_32x32x16_bf16 a[16:31], v[198:201], v[36:39], a[16:31]
	v_mfma_f32_32x32x16_bf16 a[0:15], v[198:201], v[194:197], a[0:15]
.Lrs1_skip:
	s_add_i32 s7, s6, 64
	s_min_u32 s8, s7, 0xae0
	s_lshl_b32 s78, s8, 1
	v_lshl_add_u64 v[60:61], v[100:101], 0, s[78:79]
	global_load_dwordx4 v[64:67], v[60:61], off
	s_waitcnt lgkmcnt(3)
	v_mfma_f32_32x32x16_bf16 a[48:63], v[96:99], v[52:55], a[48:63]
	ds_read_b128 v[36:39], v117 offset:0
	v_lshl_add_u64 v[62:63], v[104:105], 0, s[78:79]
	global_load_dwordx4 v[60:63], v[62:63], off
	v_mfma_f32_32x32x16_bf16 a[64:79], v[96:99], v[48:51], a[64:79]
	ds_read_b128 v[40:43], v117 offset:0x800
	v_lshl_add_u64 v[68:69], v[106:107], 0, s[78:79]
	global_load_dwordx4 v[72:75], v[68:69], off
	v_mfma_f32_32x32x16_bf16 a[80:95], v[96:99], v[44:47], a[80:95]
	ds_read_b128 v[120:123], v117 offset:0x1000
	v_lshl_add_u64 v[70:71], v[108:109], 0, s[78:79]
	global_load_dwordx4 v[68:71], v[70:71], off
	s_waitcnt lgkmcnt(5)
	v_mfma_f32_32x32x16_bf16 a[96:111], v[92:95], v[52:55], a[96:111]
	ds_read_b128 v[124:127], v115 offset:0
	v_lshl_add_u64 v[76:77], v[102:103], 0, s[78:79]
	global_load_dwordx4 v[84:87], v[76:77], off
	v_mfma_f32_32x32x16_bf16 a[112:127], v[92:95], v[48:51], a[112:127]
	ds_read_b128 v[128:131], v115 offset:0x800
	v_lshl_add_u64 v[78:79], v[110:111], 0, s[78:79]
	global_load_dwordx4 v[76:79], v[78:79], off
	v_mfma_f32_32x32x16_bf16 a[128:143], v[92:95], v[44:47], a[128:143]
	ds_read_b128 v[132:135], v115 offset:0x1000
	v_lshl_add_u64 v[80:81], v[112:113], 0, s[78:79]
	global_load_dwordx4 v[80:83], v[80:81], off
	s_min_u32 s6, s6, 0xa80
	s_lshl_b32 s78, s6, 1
	s_waitcnt lgkmcnt(7)
	v_mfma_f32_32x32x16_bf16 a[144:159], v[88:91], v[52:55], a[144:159]
	ds_read_b128 v[136:139], v115 offset:0x1800
	s_add_i32 s8, s78, 0xc0
	s_mov_b32 s9, s79
	v_mfma_f32_32x32x16_bf16 a[160:175], v[88:91], v[48:51], a[160:175]
	s_add_i32 s5, s5, 2
	s_cmpk_lt_u32 s5, 0x56
	v_mfma_f32_32x32x16_bf16 a[176:191], v[88:91], v[44:47], a[176:191]
	s_waitcnt lgkmcnt(7)
	v_mfma_f32_32x32x16_bf16 a[32:47], v[56:59], v[52:55], a[32:47]
	v_mfma_f32_32x32x16_bf16 a[16:31], v[56:59], v[48:51], a[16:31]
	s_waitcnt vmcnt(13)
	ds_write_b128 v118, v[4:7] offset:0x8000
	v_mfma_f32_32x32x16_bf16 a[0:15], v[56:59], v[44:47], a[0:15]
	s_waitcnt vmcnt(12)
	ds_write_b128 v118, v[8:11] offset:0x9000
	s_waitcnt lgkmcnt(5)
	v_mfma_f32_32x32x16_bf16 a[48:63], v[124:127], v[36:39], a[48:63]
	s_waitcnt vmcnt(11)
	ds_write_b128 v118, v[12:15] offset:0xa000
	v_mfma_f32_32x32x16_bf16 a[64:79], v[124:127], v[40:43], a[64:79]
	s_waitcnt vmcnt(10)
	ds_write_b128 v118, v[16:19] offset:0xb000
	v_mfma_f32_32x32x16_bf16 a[80:95], v[124:127], v[120:123], a[80:95]
	s_waitcnt vmcnt(9)
	ds_write_b128 v118, v[20:23] offset:0xc000
	s_waitcnt lgkmcnt(7)
	v_mfma_f32_32x32x16_bf16 a[96:111], v[128:131], v[36:39], a[96:111]
	s_waitcnt vmcnt(8)
	ds_write_b128 v118, v[24:27] offset:0xd000
	v_mfma_f32_32x32x16_bf16 a[112:127], v[128:131], v[40:43], a[112:127]
	s_waitcnt vmcnt(7)
	ds_write_b128 v118, v[28:31] offset:0xe000
	v_mfma_f32_32x32x16_bf16 a[128:143], v[128:131], v[120:123], a[128:143]
	v_lshl_add_u64 v[4:5], v[100:101], 0, s[78:79]
	v_lshl_add_u64 v[8:9], v[104:105], 0, s[8:9]
	s_waitcnt lgkmcnt(8)
	v_mfma_f32_32x32x16_bf16 a[144:159], v[132:135], v[36:39], a[144:159]
	v_lshl_add_u64 v[12:13], v[106:107], 0, s[8:9]
	v_lshl_add_u64 v[16:17], v[108:109], 0, s[8:9]
	v_mfma_f32_32x32x16_bf16 a[160:175], v[132:135], v[40:43], a[160:175]
	v_lshl_add_u64 v[20:21], v[102:103], 0, s[78:79]
	v_lshl_add_u64 v[24:25], v[110:111], 0, s[8:9]
	v_mfma_f32_32x32x16_bf16 a[176:191], v[132:135], v[120:123], a[176:191]
	v_lshl_add_u64 v[28:29], v[112:113], 0, s[8:9]
	s_waitcnt lgkmcnt(0)
	s_barrier
	ds_read_b128 v[44:47], v116 offset:0x8000
	ds_read_b128 v[48:51], v116 offset:0x8800
	ds_read_b128 v[52:55], v116 offset:0x9000
	ds_read_b128 v[56:59], v114 offset:0x8000
	ds_read_b128 v[88:91], v114 offset:0x8800
	ds_read_b128 v[92:95], v114 offset:0x9000
	ds_read_b128 v[96:99], v114 offset:0x9800
	v_mfma_f32_32x32x16_bf16 a[32:47], v[136:139], v[36:39], a[32:47]
	v_mfma_f32_32x32x16_bf16 a[16:31], v[136:139], v[40:43], a[16:31]
	v_mfma_f32_32x32x16_bf16 a[0:15], v[136:139], v[120:123], a[0:15]
	global_load_dwordx4 v[4:7], v[4:5], off offset:192
	s_waitcnt lgkmcnt(3)
	v_mfma_f32_32x32x16_bf16 a[48:63], v[56:59], v[44:47], a[48:63]
	ds_read_b128 v[40:43], v117 offset:0x8000
	global_load_dwordx4 v[8:11], v[8:9], off
	v_mfma_f32_32x32x16_bf16 a[64:79], v[56:59], v[48:51], a[64:79]
	ds_read_b128 v[36:39], v117 offset:0x8800
	global_load_dwordx4 v[12:15], v[12:13], off
	v_mfma_f32_32x32x16_bf16 a[80:95], v[56:59], v[52:55], a[80:95]
	ds_read_b128 v[194:197], v117 offset:0x9000
	global_load_dwordx4 v[16:19], v[16:17], off
	s_waitcnt lgkmcnt(5)
	v_mfma_f32_32x32x16_bf16 a[96:111], v[88:91], v[44:47], a[96:111]
	ds_read_b128 v[120:123], v115 offset:0x8000
	global_load_dwordx4 v[20:23], v[20:21], off offset:192
	v_mfma_f32_32x32x16_bf16 a[112:127], v[88:91], v[48:51], a[112:127]
	ds_read_b128 v[124:127], v115 offset:0x8800
	global_load_dwordx4 v[24:27], v[24:25], off
	v_mfma_f32_32x32x16_bf16 a[128:143], v[88:91], v[52:55], a[128:143]
	ds_read_b128 v[128:131], v115 offset:0x9000
	global_load_dwordx4 v[28:31], v[28:29], off
	s_waitcnt lgkmcnt(7)
	v_mfma_f32_32x32x16_bf16 a[144:159], v[92:95], v[44:47], a[144:159]
	ds_read_b128 v[198:201], v115 offset:0x9800
	v_mfma_f32_32x32x16_bf16 a[160:175], v[92:95], v[48:51], a[160:175]
	v_mfma_f32_32x32x16_bf16 a[176:191], v[92:95], v[52:55], a[176:191]
	s_waitcnt lgkmcnt(7)
	v_mfma_f32_32x32x16_bf16 a[32:47], v[96:99], v[44:47], a[32:47]
	v_mfma_f32_32x32x16_bf16 a[16:31], v[96:99], v[48:51], a[16:31]
	v_mfma_f32_32x32x16_bf16 a[0:15], v[96:99], v[52:55], a[0:15]
	s_waitcnt lgkmcnt(3)
	v_mfma_f32_32x32x16_bf16 a[48:63], v[120:123], v[40:43], a[48:63]
	s_waitcnt vmcnt(13)
	ds_write_b128 v118, v[64:67] offset:0
	v_mfma_f32_32x32x16_bf16 a[64:79], v[120:123], v[36:39], a[64:79]
	s_waitcnt vmcnt(12)
	ds_write_b128 v118, v[60:63] offset:0x1000
	v_mfma_f32_32x32x16_bf16 a[80:95], v[120:123], v[194:197], a[80:95]
	s_waitcnt vmcnt(11)
	ds_write_b128 v118, v[72:75] offset:0x2000
	s_waitcnt lgkmcnt(5)
	v_mfma_f32_32x32x16_bf16 a[96:111], v[124:127], v[40:43], a[96:111]
	s_waitcnt vmcnt(10)
	ds_write_b128 v118, v[68:71] offset:0x3000
	v_mfma_f32_32x32x16_bf16 a[112:127], v[124:127], v[36:39], a[112:127]
	s_waitcnt vmcnt(9)
	ds_write_b128 v118, v[84:87] offset:0x4000
	v_mfma_f32_32x32x16_bf16 a[128:143], v[124:127], v[194:197], a[128:143]
	s_waitcnt vmcnt(8)
	ds_write_b128 v118, v[76:79] offset:0x5000
	s_waitcnt lgkmcnt(7)
	v_mfma_f32_32x32x16_bf16 a[144:159], v[128:131], v[40:43], a[144:159]
	s_waitcnt vmcnt(7)
	ds_write_b128 v118, v[80:83] offset:0x6000
	v_mfma_f32_32x32x16_bf16 a[160:175], v[128:131], v[36:39], a[160:175]
	v_mfma_f32_32x32x16_bf16 a[176:191], v[128:131], v[194:197], a[176:191]
	s_waitcnt lgkmcnt(0)
	s_barrier
	s_cbranch_scc0 .LBB0_120
	s_mov_b32 s6, s7
	s_branch .Lrs1_top

.LBB0_141:
.Lrs2_top:
	s_cmp_eq_u32 s4, 0
	ds_read_b128 v[48:51], v82 offset:0
	ds_read_b128 v[44:47], v82 offset:0x800
	ds_read_b128 v[64:67], v80 offset:0
	ds_read_b128 v[60:63], v80 offset:0x800
	ds_read_b128 v[56:59], v80 offset:0x1000
	ds_read_b128 v[52:55], v80 offset:0x1800
	s_cbranch_scc1 .Lrs2_skip
	v_mfma_f32_32x32x16_bf16 a[16:31], v[132:135], v[40:43], a[16:31]
	v_mfma_f32_32x32x16_bf16 a[0:15], v[132:135], v[128:131], a[0:15]
.Lrs2_skip:
	s_add_i32 s5, s4, 64
	s_min_u32 s6, s5, 0xae0
	s_lshl_b32 s78, s6, 1
	v_lshl_add_u64 v[106:107], v[68:69], 0, s[78:79]
	global_load_dwordx4 v[106:109], v[106:107], off
	s_waitcnt lgkmcnt(3)
	v_mfma_f32_32x32x16_bf16 a[32:47], v[64:67], v[48:51], a[32:47]
	ds_read_b128 v[40:43], v83 offset:0
	v_lshl_add_u64 v[110:111], v[72:73], 0, s[78:79]
	global_load_dwordx4 v[110:113], v[110:111], off
	v_mfma_f32_32x32x16_bf16 a[48:63], v[64:67], v[44:47], a[48:63]
	ds_read_b128 v[86:89], v83 offset:0x800
	v_lshl_add_u64 v[114:115], v[74:75], 0, s[78:79]
	global_load_dwordx4 v[114:117], v[114:115], off
	s_waitcnt lgkmcnt(4)
	v_mfma_f32_32x32x16_bf16 a[64:79], v[60:63], v[48:51], a[64:79]
	ds_read_b128 v[90:93], v81 offset:0
	v_lshl_add_u64 v[118:119], v[76:77], 0, s[78:79]
	global_load_dwordx4 v[118:121], v[118:119], off
	v_mfma_f32_32x32x16_bf16 a[80:95], v[60:63], v[44:47], a[80:95]
	ds_read_b128 v[94:97], v81 offset:0x800
	v_lshl_add_u64 v[122:123], v[70:71], 0, s[78:79]
	global_load_dwordx4 v[122:125], v[122:123], off
	s_waitcnt lgkmcnt(5)
	v_mfma_f32_32x32x16_bf16 a[96:111], v[56:59], v[48:51], a[96:111]
	ds_read_b128 v[98:101], v81 offset:0x1000
	v_lshl_add_u64 v[126:127], v[78:79], 0, s[78:79]
	global_load_dwordx4 v[140:143], v[126:127], off
	s_min_u32 s4, s4, 0xa80
	s_lshl_b32 s78, s4, 1
	v_mfma_f32_32x32x16_bf16 a[112:127], v[56:59], v[44:47], a[112:127]
	ds_read_b128 v[102:105], v81 offset:0x1800
	s_add_i32 s6, s78, 0xc0
	s_mov_b32 s7, s79
	s_waitcnt lgkmcnt(6)
	v_mfma_f32_32x32x16_bf16 a[16:31], v[52:55], v[48:51], a[16:31]
	s_add_i32 s3, s3, 2
	s_cmpk_lt_u32 s3, 0x56
	s_waitcnt vmcnt(11)
	ds_write_b128 v84, v[4:7] offset:0x8000
	v_mfma_f32_32x32x16_bf16 a[0:15], v[52:55], v[44:47], a[0:15]
	s_waitcnt vmcnt(10)
	ds_write_b128 v84, v[8:11] offset:0x9000
	s_waitcnt lgkmcnt(5)
	v_mfma_f32_32x32x16_bf16 a[32:47], v[90:93], v[40:43], a[32:47]
	s_waitcnt vmcnt(9)
	ds_write_b128 v84, v[12:15] offset:0xa000
	v_mfma_f32_32x32x16_bf16 a[48:63], v[90:93], v[86:89], a[48:63]
	s_waitcnt vmcnt(8)
	ds_write_b128 v84, v[16:19] offset:0xb000
	s_waitcnt lgkmcnt(6)
	v_mfma_f32_32x32x16_bf16 a[64:79], v[94:97], v[40:43], a[64:79]
	s_waitcnt vmcnt(7)
	ds_write_b128 v84, v[20:23] offset:0xc000
	v_mfma_f32_32x32x16_bf16 a[80:95], v[94:97], v[86:89], a[80:95]
	s_waitcnt vmcnt(6)
	ds_write_b128 v84, v[24:27] offset:0xd000
	s_waitcnt lgkmcnt(7)
	v_mfma_f32_32x32x16_bf16 a[96:111], v[98:101], v[40:43], a[96:111]
	v_lshl_add_u64 v[4:5], v[68:69], 0, s[78:79]
	v_lshl_add_u64 v[8:9], v[72:73], 0, s[6:7]
	v_lshl_add_u64 v[12:13], v[74:75], 0, s[6:7]
	v_mfma_f32_32x32x16_bf16 a[112:127], v[98:101], v[86:89], a[112:127]
	v_lshl_add_u64 v[16:17], v[76:77], 0, s[6:7]
	v_lshl_add_u64 v[20:21], v[70:71], 0, s[78:79]
	v_lshl_add_u64 v[24:25], v[78:79], 0, s[6:7]
	s_waitcnt lgkmcnt(0)
	s_barrier
	ds_read_b128 v[44:47], v82 offset:0x8000
	ds_read_b128 v[48:51], v82 offset:0x8800
	ds_read_b128 v[52:55], v80 offset:0x8000
	ds_read_b128 v[56:59], v80 offset:0x8800
	ds_read_b128 v[60:63], v80 offset:0x9000
	ds_read_b128 v[64:67], v80 offset:0x9800
	v_mfma_f32_32x32x16_bf16 a[16:31], v[102:105], v[40:43], a[16:31]
	v_mfma_f32_32x32x16_bf16 a[0:15], v[102:105], v[86:89], a[0:15]
	global_load_dwordx4 v[4:7], v[4:5], off offset:192
	s_waitcnt lgkmcnt(3)
	v_mfma_f32_32x32x16_bf16 a[32:47], v[52:55], v[44:47], a[32:47]
	ds_read_b128 v[40:43], v83 offset:0x8000
	global_load_dwordx4 v[8:11], v[8:9], off
	v_mfma_f32_32x32x16_bf16 a[48:63], v[52:55], v[48:51], a[48:63]
	ds_read_b128 v[128:131], v83 offset:0x8800
	global_load_dwordx4 v[12:15], v[12:13], off
	s_waitcnt lgkmcnt(4)
	v_mfma_f32_32x32x16_bf16 a[64:79], v[56:59], v[44:47], a[64:79]
	ds_read_b128 v[86:89], v81 offset:0x8000
	global_load_dwordx4 v[16:19], v[16:17], off
	v_mfma_f32_32x32x16_bf16 a[80:95], v[56:59], v[48:51], a[80:95]
	ds_read_b128 v[90:93], v81 offset:0x8800
	global_load_dwordx4 v[20:23], v[20:21], off offset:192
	s_waitcnt lgkmcnt(5)
	v_mfma_f32_32x32x16_bf16 a[96:111], v[60:63], v[44:47], a[96:111]
	ds_read_b128 v[94:97], v81 offset:0x9000
	global_load_dwordx4 v[24:27], v[24:25], off
	v_mfma_f32_32x32x16_bf16 a[112:127], v[60:63], v[48:51], a[112:127]
	ds_read_b128 v[132:135], v81 offset:0x9800
	s_waitcnt lgkmcnt(6)
	v_mfma_f32_32x32x16_bf16 a[16:31], v[64:67], v[44:47], a[16:31]
	s_waitcnt vmcnt(11)
	ds_write_b128 v84, v[106:109] offset:0
	v_mfma_f32_32x32x16_bf16 a[0:15], v[64:67], v[48:51], a[0:15]
	s_waitcnt vmcnt(10)
	ds_write_b128 v84, v[110:113] offset:0x1000
	s_waitcnt lgkmcnt(5)
	v_mfma_f32_32x32x16_bf16 a[32:47], v[86:89], v[40:43], a[32:47]
	s_waitcnt vmcnt(9)
	ds_write_b128 v84, v[114:117] offset:0x2000
	v_mfma_f32_32x32x16_bf16 a[48:63], v[86:89], v[128:131], a[48:63]
	s_waitcnt vmcnt(8)
	ds_write_b128 v84, v[118:121] offset:0x3000
	s_waitcnt lgkmcnt(6)
	v_mfma_f32_32x32x16_bf16 a[64:79], v[90:93], v[40:43], a[64:79]
	s_waitcnt vmcnt(7)
	ds_write_b128 v84, v[122:125] offset:0x4000
	v_mfma_f32_32x32x16_bf16 a[80:95], v[90:93], v[128:131], a[80:95]
	s_waitcnt vmcnt(6)
	ds_write_b128 v84, v[140:143] offset:0x5000
	s_waitcnt lgkmcnt(7)
	v_mfma_f32_32x32x16_bf16 a[96:111], v[94:97], v[40:43], a[96:111]
	v_mfma_f32_32x32x16_bf16 a[112:127], v[94:97], v[128:131], a[112:127]
	s_waitcnt lgkmcnt(0)
	s_barrier
	s_cbranch_scc0 .LBB0_139
	s_mov_b32 s4, s5
	s_branch .Lrs2_top

.LBB0_162:
.Lrs0_top:
	s_cmp_eq_u32 s4, 0
	ds_read_b128 v[44:47], v116 offset:0
	ds_read_b128 v[40:43], v116 offset:0x800
	ds_read_b128 v[36:39], v116 offset:0x1000
	ds_read_b128 v[92:95], v110 offset:0
	ds_read_b128 v[88:91], v110 offset:0x800
	ds_read_b128 v[84:87], v110 offset:0x1000
	ds_read_b128 v[48:51], v110 offset:0x1800
	s_cbranch_scc1 .Lrs0_skip
	v_mfma_f32_32x32x16_bf16 a[32:47], v[132:135], v[80:83], a[32:47]
	v_mfma_f32_32x32x16_bf16 a[16:31], v[132:135], v[112:115], a[16:31]
	v_mfma_f32_32x32x16_bf16 a[0:15], v[132:135], v[128:131], a[0:15]
.Lrs0_skip:
	s_add_i32 s5, s4, 64
	s_min_u32 s6, s5, 0x3e0
	s_lshl_b32 s78, s6, 1
	v_lshl_add_u64 v[52:53], v[96:97], 0, s[78:79]
	global_load_dwordx4 v[56:59], v[52:53], off
	s_waitcnt lgkmcnt(3)
	v_mfma_f32_32x32x16_bf16 a[80:95], v[92:95], v[44:47], a[80:95]
	ds_read_b128 v[80:83], v117 offset:0
	v_lshl_add_u64 v[54:55], v[100:101], 0, s[78:79]
	global_load_dwordx4 v[52:55], v[54:55], off
	v_mfma_f32_32x32x16_bf16 a[48:63], v[92:95], v[40:43], a[48:63]
	ds_read_b128 v[112:115], v117 offset:0x800
	v_lshl_add_u64 v[60:61], v[102:103], 0, s[78:79]
	global_load_dwordx4 v[64:67], v[60:61], off
	v_mfma_f32_32x32x16_bf16 a[64:79], v[92:95], v[36:39], a[64:79]
	ds_read_b128 v[120:123], v117 offset:0x1000
	v_lshl_add_u64 v[62:63], v[104:105], 0, s[78:79]
	global_load_dwordx4 v[60:63], v[62:63], off
	s_waitcnt lgkmcnt(5)
	v_mfma_f32_32x32x16_bf16 a[96:111], v[88:91], v[44:47], a[96:111]
	ds_read_b128 v[124:127], v111 offset:0
	v_lshl_add_u64 v[68:69], v[98:99], 0, s[78:79]
	global_load_dwordx4 v[76:79], v[68:69], off
	v_mfma_f32_32x32x16_bf16 a[112:127], v[88:91], v[40:43], a[112:127]
	ds_read_b128 v[128:131], v111 offset:0x800
	v_lshl_add_u64 v[70:71], v[106:107], 0, s[78:79]
	global_load_dwordx4 v[68:71], v[70:71], off
	v_mfma_f32_32x32x16_bf16 a[128:143], v[88:91], v[36:39], a[128:143]
	ds_read_b128 v[132:135], v111 offset:0x1000
	v_lshl_add_u64 v[72:73], v[108:109], 0, s[78:79]
	global_load_dwordx4 v[72:75], v[72:73], off
	s_min_u32 s4, s4, 0x380
	s_lshl_b32 s78, s4, 1
	s_waitcnt lgkmcnt(7)
	v_mfma_f32_32x32x16_bf16 a[144:159], v[84:87], v[44:47], a[144:159]
	ds_read_b128 v[136:139], v111 offset:0x1800
	s_add_i32 s6, s78, 0xc0
	s_mov_b32 s7, s79
	v_mfma_f32_32x32x16_bf16 a[160:175], v[84:87], v[40:43], a[160:175]
	s_add_i32 s3, s3, 2
	s_cmp_lt_u32 s3, 30
	v_mfma_f32_32x32x16_bf16 a[176:191], v[84:87], v[36:39], a[176:191]
	s_waitcnt lgkmcnt(7)
	v_mfma_f32_32x32x16_bf16 a[32:47], v[48:51], v[44:47], a[32:47]
	v_mfma_f32_32x32x16_bf16 a[16:31], v[48:51], v[40:43], a[16:31]
	s_waitcnt vmcnt(13)
	ds_write_b128 v118, v[4:7] offset:0x8000
	v_mfma_f32_32x32x16_bf16 a[0:15], v[48:51], v[36:39], a[0:15]
	s_waitcnt vmcnt(12)
	ds_write_b128 v118, v[8:11] offset:0x9000
	s_waitcnt lgkmcnt(5)
	v_mfma_f32_32x32x16_bf16 a[80:95], v[124:127], v[80:83], a[80:95]
	s_waitcnt vmcnt(11)
	ds_write_b128 v118, v[12:15] offset:0xa000
	v_mfma_f32_32x32x16_bf16 a[48:63], v[124:127], v[112:115], a[48:63]
	s_waitcnt vmcnt(10)
	ds_write_b128 v118, v[16:19] offset:0xb000
	v_mfma_f32_32x32x16_bf16 a[64:79], v[124:127], v[120:123], a[64:79]
	s_waitcnt vmcnt(9)
	ds_write_b128 v118, v[20:23] offset:0xc000
	s_waitcnt lgkmcnt(7)
	v_mfma_f32_32x32x16_bf16 a[96:111], v[128:131], v[80:83], a[96:111]
	s_waitcnt vmcnt(8)
	ds_write_b128 v118, v[24:27] offset:0xd000
	v_mfma_f32_32x32x16_bf16 a[112:127], v[128:131], v[112:115], a[112:127]
	s_waitcnt vmcnt(7)
	ds_write_b128 v118, v[28:31] offset:0xe000
	v_mfma_f32_32x32x16_bf16 a[128:143], v[128:131], v[120:123], a[128:143]
	v_lshl_add_u64 v[4:5], v[96:97], 0, s[78:79]
	v_lshl_add_u64 v[8:9], v[100:101], 0, s[6:7]
	s_waitcnt lgkmcnt(8)
	v_mfma_f32_32x32x16_bf16 a[144:159], v[132:135], v[80:83], a[144:159]
	v_lshl_add_u64 v[12:13], v[102:103], 0, s[6:7]
	v_lshl_add_u64 v[16:17], v[104:105], 0, s[6:7]
	v_mfma_f32_32x32x16_bf16 a[160:175], v[132:135], v[112:115], a[160:175]
	v_lshl_add_u64 v[20:21], v[98:99], 0, s[78:79]
	v_lshl_add_u64 v[24:25], v[106:107], 0, s[6:7]
	v_mfma_f32_32x32x16_bf16 a[176:191], v[132:135], v[120:123], a[176:191]
	v_lshl_add_u64 v[28:29], v[108:109], 0, s[6:7]
	s_waitcnt lgkmcnt(0)
	s_barrier
	ds_read_b128 v[36:39], v116 offset:0x8000
	ds_read_b128 v[40:43], v116 offset:0x8800
	ds_read_b128 v[44:47], v116 offset:0x9000
	ds_read_b128 v[48:51], v110 offset:0x8000
	ds_read_b128 v[84:87], v110 offset:0x8800
	ds_read_b128 v[88:91], v110 offset:0x9000
	ds_read_b128 v[92:95], v110 offset:0x9800
	v_mfma_f32_32x32x16_bf16 a[32:47], v[136:139], v[80:83], a[32:47]
	v_mfma_f32_32x32x16_bf16 a[16:31], v[136:139], v[112:115], a[16:31]
	v_mfma_f32_32x32x16_bf16 a[0:15], v[136:139], v[120:123], a[0:15]
	global_load_dwordx4 v[4:7], v[4:5], off offset:192
	s_waitcnt lgkmcnt(3)
	v_mfma_f32_32x32x16_bf16 a[80:95], v[48:51], v[36:39], a[80:95]
	ds_read_b128 v[80:83], v117 offset:0x8000
	global_load_dwordx4 v[8:11], v[8:9], off
	v_mfma_f32_32x32x16_bf16 a[48:63], v[48:51], v[40:43], a[48:63]
	ds_read_b128 v[112:115], v117 offset:0x8800
	global_load_dwordx4 v[12:15], v[12:13], off
	v_mfma_f32_32x32x16_bf16 a[64:79], v[48:51], v[44:47], a[64:79]
	ds_read_b128 v[128:131], v117 offset:0x9000
	global_load_dwordx4 v[16:19], v[16:17], off
	s_waitcnt lgkmcnt(5)
	v_mfma_f32_32x32x16_bf16 a[96:111], v[84:87], v[36:39], a[96:111]
	ds_read_b128 v[120:123], v111 offset:0x8000
	global_load_dwordx4 v[20:23], v[20:21], off offset:192
	v_mfma_f32_32x32x16_bf16 a[112:127], v[84:87], v[40:43], a[112:127]
	ds_read_b128 v[124:127], v111 offset:0x8800
	global_load_dwordx4 v[24:27], v[24:25], off
	v_mfma_f32_32x32x16_bf16 a[128:143], v[84:87], v[44:47], a[128:143]
	ds_read_b128 v[136:139], v111 offset:0x9000
	global_load_dwordx4 v[28:31], v[28:29], off
	s_waitcnt lgkmcnt(7)
	v_mfma_f32_32x32x16_bf16 a[144:159], v[88:91], v[36:39], a[144:159]
	ds_read_b128 v[132:135], v111 offset:0x9800
	v_mfma_f32_32x32x16_bf16 a[160:175], v[88:91], v[40:43], a[160:175]
	v_mfma_f32_32x32x16_bf16 a[176:191], v[88:91], v[44:47], a[176:191]
	s_waitcnt lgkmcnt(7)
	v_mfma_f32_32x32x16_bf16 a[32:47], v[92:95], v[36:39], a[32:47]
	v_mfma_f32_32x32x16_bf16 a[16:31], v[92:95], v[40:43], a[16:31]
	v_mfma_f32_32x32x16_bf16 a[0:15], v[92:95], v[44:47], a[0:15]
	s_waitcnt lgkmcnt(3)
	v_mfma_f32_32x32x16_bf16 a[80:95], v[120:123], v[80:83], a[80:95]
	s_waitcnt vmcnt(13)
	ds_write_b128 v118, v[56:59] offset:0
	v_mfma_f32_32x32x16_bf16 a[48:63], v[120:123], v[112:115], a[48:63]
	s_waitcnt vmcnt(12)
	ds_write_b128 v118, v[52:55] offset:0x1000
	v_mfma_f32_32x32x16_bf16 a[64:79], v[120:123], v[128:131], a[64:79]
	s_waitcnt vmcnt(11)
	ds_write_b128 v118, v[64:67] offset:0x2000
	s_waitcnt lgkmcnt(5)
	v_mfma_f32_32x32x16_bf16 a[96:111], v[124:127], v[80:83], a[96:111]
	s_waitcnt vmcnt(10)
	ds_write_b128 v118, v[60:63] offset:0x3000
	v_mfma_f32_32x32x16_bf16 a[112:127], v[124:127], v[112:115], a[112:127]
	s_waitcnt vmcnt(9)
	ds_write_b128 v118, v[76:79] offset:0x4000
	v_mfma_f32_32x32x16_bf16 a[128:143], v[124:127], v[128:131], a[128:143]
	s_waitcnt vmcnt(8)
	ds_write_b128 v118, v[68:71] offset:0x5000
	s_waitcnt lgkmcnt(7)
	v_mfma_f32_32x32x16_bf16 a[144:159], v[136:139], v[80:83], a[144:159]
	s_waitcnt vmcnt(7)
	ds_write_b128 v118, v[72:75] offset:0x6000
	v_mfma_f32_32x32x16_bf16 a[160:175], v[136:139], v[112:115], a[160:175]
	v_mfma_f32_32x32x16_bf16 a[176:191], v[136:139], v[128:131], a[176:191]
	s_waitcnt lgkmcnt(0)
	s_barrier
	s_cbranch_scc0 .LBB0_160
	s_mov_b32 s4, s5
	s_branch .Lrs0_top

.Lrs3_skip:
	s_add_i32 s7, s6, 64
	s_min_u32 s8, s7, 0x3e0
	s_lshl_b32 s78, s8, 1
	v_lshl_add_u64 v[60:61], v[100:101], 0, s[78:79]
	global_load_dwordx4 v[64:67], v[60:61], off
	s_waitcnt lgkmcnt(3)
	v_mfma_f32_32x32x16_bf16 a[48:63], v[96:99], v[52:55], a[48:63]
	ds_read_b128 v[36:39], v117 offset:0
	v_lshl_add_u64 v[62:63], v[104:105], 0, s[78:79]
	global_load_dwordx4 v[60:63], v[62:63], off
	v_mfma_f32_32x32x16_bf16 a[64:79], v[96:99], v[48:51], a[64:79]
	ds_read_b128 v[40:43], v117 offset:0x800
	v_lshl_add_u64 v[68:69], v[106:107], 0, s[78:79]
	global_load_dwordx4 v[72:75], v[68:69], off
	v_mfma_f32_32x32x16_bf16 a[80:95], v[96:99], v[44:47], a[80:95]
	ds_read_b128 v[120:123], v117 offset:0x1000
	v_lshl_add_u64 v[70:71], v[108:109], 0, s[78:79]
	global_load_dwordx4 v[68:71], v[70:71], off
	s_waitcnt lgkmcnt(5)
	v_mfma_f32_32x32x16_bf16 a[96:111], v[92:95], v[52:55], a[96:111]
	ds_read_b128 v[124:127], v115 offset:0
	v_lshl_add_u64 v[76:77], v[102:103], 0, s[78:79]
	global_load_dwordx4 v[84:87], v[76:77], off
	v_mfma_f32_32x32x16_bf16 a[112:127], v[92:95], v[48:51], a[112:127]
	ds_read_b128 v[128:131], v115 offset:0x800
	v_lshl_add_u64 v[78:79], v[110:111], 0, s[78:79]
	global_load_dwordx4 v[76:79], v[78:79], off
	v_mfma_f32_32x32x16_bf16 a[128:143], v[92:95], v[44:47], a[128:143]
	ds_read_b128 v[132:135], v115 offset:0x1000
	v_lshl_add_u64 v[80:81], v[112:113], 0, s[78:79]
	global_load_dwordx4 v[80:83], v[80:81], off
	s_min_u32 s6, s6, 0x380
	s_lshl_b32 s78, s6, 1
	s_waitcnt lgkmcnt(7)
	v_mfma_f32_32x32x16_bf16 a[144:159], v[88:91], v[52:55], a[144:159]
	ds_read_b128 v[136:139], v115 offset:0x1800
	s_add_i32 s8, s78, 0xc0
	s_mov_b32 s9, s79
	v_mfma_f32_32x32x16_bf16 a[160:175], v[88:91], v[48:51], a[160:175]
	s_add_i32 s5, s5, 2
	s_cmp_lt_u32 s5, 30
	v_mfma_f32_32x32x16_bf16 a[176:191], v[88:91], v[44:47], a[176:191]
	s_waitcnt lgkmcnt(7)
	v_mfma_f32_32x32x16_bf16 a[32:47], v[56:59], v[52:55], a[32:47]
	v_mfma_f32_32x32x16_bf16 a[16:31], v[56:59], v[48:51], a[16:31]
	s_waitcnt vmcnt(13)
	ds_write_b128 v118, v[4:7] offset:0x8000
	v_mfma_f32_32x32x16_bf16 a[0:15], v[56:59], v[44:47], a[0:15]
	s_waitcnt vmcnt(12)
	ds_write_b128 v118, v[8:11] offset:0x9000
	s_waitcnt lgkmcnt(5)
	v_mfma_f32_32x32x16_bf16 a[48:63], v[124:127], v[36:39], a[48:63]
	s_waitcnt vmcnt(11)
	ds_write_b128 v118, v[12:15] offset:0xa000
	v_mfma_f32_32x32x16_bf16 a[64:79], v[124:127], v[40:43], a[64:79]
	s_waitcnt vmcnt(10)
	ds_write_b128 v118, v[16:19] offset:0xb000
	v_mfma_f32_32x32x16_bf16 a[80:95], v[124:127], v[120:123], a[80:95]
	s_waitcnt vmcnt(9)
	ds_write_b128 v118, v[20:23] offset:0xc000
	s_waitcnt lgkmcnt(7)
	v_mfma_f32_32x32x16_bf16 a[96:111], v[128:131], v[36:39], a[96:111]
	s_waitcnt vmcnt(8)
	ds_write_b128 v118, v[24:27] offset:0xd000
	v_mfma_f32_32x32x16_bf16 a[112:127], v[128:131], v[40:43], a[112:127]
	s_waitcnt vmcnt(7)
	ds_write_b128 v118, v[28:31] offset:0xe000
	v_mfma_f32_32x32x16_bf16 a[128:143], v[128:131], v[120:123], a[128:143]
	v_lshl_add_u64 v[4:5], v[100:101], 0, s[78:79]
	v_lshl_add_u64 v[8:9], v[104:105], 0, s[8:9]
	s_waitcnt lgkmcnt(8)
	v_mfma_f32_32x32x16_bf16 a[144:159], v[132:135], v[36:39], a[144:159]
	v_lshl_add_u64 v[12:13], v[106:107], 0, s[8:9]
	v_lshl_add_u64 v[16:17], v[108:109], 0, s[8:9]
	v_mfma_f32_32x32x16_bf16 a[160:175], v[132:135], v[40:43], a[160:175]
	v_lshl_add_u64 v[20:21], v[102:103], 0, s[78:79]
	v_lshl_add_u64 v[24:25], v[110:111], 0, s[8:9]
	v_mfma_f32_32x32x16_bf16 a[176:191], v[132:135], v[120:123], a[176:191]
	v_lshl_add_u64 v[28:29], v[112:113], 0, s[8:9]
	s_waitcnt lgkmcnt(0)
	s_barrier
	ds_read_b128 v[44:47], v116 offset:0x8000
	ds_read_b128 v[48:51], v116 offset:0x8800
	ds_read_b128 v[52:55], v116 offset:0x9000
	ds_read_b128 v[56:59], v114 offset:0x8000
	ds_read_b128 v[88:91], v114 offset:0x8800
	ds_read_b128 v[92:95], v114 offset:0x9000
	ds_read_b128 v[96:99], v114 offset:0x9800
	v_mfma_f32_32x32x16_bf16 a[32:47], v[136:139], v[36:39], a[32:47]
	v_mfma_f32_32x32x16_bf16 a[16:31], v[136:139], v[40:43], a[16:31]
	v_mfma_f32_32x32x16_bf16 a[0:15], v[136:139], v[120:123], a[0:15]
	global_load_dwordx4 v[4:7], v[4:5], off offset:192
	s_waitcnt lgkmcnt(3)
	v_mfma_f32_32x32x16_bf16 a[48:63], v[56:59], v[44:47], a[48:63]
	ds_read_b128 v[40:43], v117 offset:0x8000
	global_load_dwordx4 v[8:11], v[8:9], off
	v_mfma_f32_32x32x16_bf16 a[64:79], v[56:59], v[48:51], a[64:79]
	ds_read_b128 v[36:39], v117 offset:0x8800
	global_load_dwordx4 v[12:15], v[12:13], off
	v_mfma_f32_32x32x16_bf16 a[80:95], v[56:59], v[52:55], a[80:95]
	ds_read_b128 v[194:197], v117 offset:0x9000
	global_load_dwordx4 v[16:19], v[16:17], off
	s_waitcnt lgkmcnt(5)
	v_mfma_f32_32x32x16_bf16 a[96:111], v[88:91], v[44:47], a[96:111]
	ds_read_b128 v[120:123], v115 offset:0x8000
	global_load_dwordx4 v[20:23], v[20:21], off offset:192
	v_mfma_f32_32x32x16_bf16 a[112:127], v[88:91], v[48:51], a[112:127]
	ds_read_b128 v[124:127], v115 offset:0x8800
	global_load_dwordx4 v[24:27], v[24:25], off
	v_mfma_f32_32x32x16_bf16 a[128:143], v[88:91], v[52:55], a[128:143]
	ds_read_b128 v[128:131], v115 offset:0x9000
	global_load_dwordx4 v[28:31], v[28:29], off
	s_waitcnt lgkmcnt(7)
	v_mfma_f32_32x32x16_bf16 a[144:159], v[92:95], v[44:47], a[144:159]
	ds_read_b128 v[198:201], v115 offset:0x9800
	v_mfma_f32_32x32x16_bf16 a[160:175], v[92:95], v[48:51], a[160:175]
	v_mfma_f32_32x32x16_bf16 a[176:191], v[92:95], v[52:55], a[176:191]
	s_waitcnt lgkmcnt(7)
	v_mfma_f32_32x32x16_bf16 a[32:47], v[96:99], v[44:47], a[32:47]
	v_mfma_f32_32x32x16_bf16 a[16:31], v[96:99], v[48:51], a[16:31]
	v_mfma_f32_32x32x16_bf16 a[0:15], v[96:99], v[52:55], a[0:15]
	s_waitcnt lgkmcnt(3)
	v_mfma_f32_32x32x16_bf16 a[48:63], v[120:123], v[40:43], a[48:63]
	s_waitcnt vmcnt(13)
	ds_write_b128 v118, v[64:67] offset:0
	v_mfma_f32_32x32x16_bf16 a[64:79], v[120:123], v[36:39], a[64:79]
	s_waitcnt vmcnt(12)
	ds_write_b128 v118, v[60:63] offset:0x1000
	v_mfma_f32_32x32x16_bf16 a[80:95], v[120:123], v[194:197], a[80:95]
	s_waitcnt vmcnt(11)
	ds_write_b128 v118, v[72:75] offset:0x2000
	s_waitcnt lgkmcnt(5)
	v_mfma_f32_32x32x16_bf16 a[96:111], v[124:127], v[40:43], a[96:111]
	s_waitcnt vmcnt(10)
	ds_write_b128 v118, v[68:71] offset:0x3000
	v_mfma_f32_32x32x16_bf16 a[112:127], v[124:127], v[36:39], a[112:127]
	s_waitcnt vmcnt(9)
	ds_write_b128 v118, v[84:87] offset:0x4000
	v_mfma_f32_32x32x16_bf16 a[128:143], v[124:127], v[194:197], a[128:143]
	s_waitcnt vmcnt(8)
	ds_write_b128 v118, v[76:79] offset:0x5000
	s_waitcnt lgkmcnt(7)
	v_mfma_f32_32x32x16_bf16 a[144:159], v[128:131], v[40:43], a[144:159]
	s_waitcnt vmcnt(7)
	ds_write_b128 v118, v[80:83] offset:0x6000
	v_mfma_f32_32x32x16_bf16 a[160:175], v[128:131], v[36:39], a[160:175]
	v_mfma_f32_32x32x16_bf16 a[176:191], v[128:131], v[194:197], a[176:191]
	s_waitcnt lgkmcnt(0)
	s_barrier
	s_cbranch_scc0 .LBB0_203
	s_mov_b32 s6, s7
	s_branch .Lrs3_top

.Lrs4_skip:
	s_add_i32 s5, s4, 64
	s_min_u32 s6, s5, 0x3e0
	s_lshl_b32 s78, s6, 1
	v_lshl_add_u64 v[106:107], v[68:69], 0, s[78:79]
	global_load_dwordx4 v[106:109], v[106:107], off
	s_waitcnt lgkmcnt(3)
	v_mfma_f32_32x32x16_bf16 a[32:47], v[64:67], v[48:51], a[32:47]
	ds_read_b128 v[40:43], v83 offset:0
	v_lshl_add_u64 v[110:111], v[72:73], 0, s[78:79]
	global_load_dwordx4 v[110:113], v[110:111], off
	v_mfma_f32_32x32x16_bf16 a[48:63], v[64:67], v[44:47], a[48:63]
	ds_read_b128 v[86:89], v83 offset:0x800
	v_lshl_add_u64 v[114:115], v[74:75], 0, s[78:79]
	global_load_dwordx4 v[114:117], v[114:115], off
	s_waitcnt lgkmcnt(4)
	v_mfma_f32_32x32x16_bf16 a[64:79], v[60:63], v[48:51], a[64:79]
	ds_read_b128 v[90:93], v81 offset:0
	v_lshl_add_u64 v[118:119], v[76:77], 0, s[78:79]
	global_load_dwordx4 v[118:121], v[118:119], off
	v_mfma_f32_32x32x16_bf16 a[80:95], v[60:63], v[44:47], a[80:95]
	ds_read_b128 v[94:97], v81 offset:0x800
	v_lshl_add_u64 v[122:123], v[70:71], 0, s[78:79]
	global_load_dwordx4 v[122:125], v[122:123], off
	s_waitcnt lgkmcnt(5)
	v_mfma_f32_32x32x16_bf16 a[96:111], v[56:59], v[48:51], a[96:111]
	ds_read_b128 v[98:101], v81 offset:0x1000
	v_lshl_add_u64 v[126:127], v[78:79], 0, s[78:79]
	global_load_dwordx4 v[140:143], v[126:127], off
	s_min_u32 s4, s4, 0x380
	s_lshl_b32 s78, s4, 1
	v_mfma_f32_32x32x16_bf16 a[112:127], v[56:59], v[44:47], a[112:127]
	ds_read_b128 v[102:105], v81 offset:0x1800
	s_add_i32 s6, s78, 0xc0
	s_mov_b32 s7, s79
	s_waitcnt lgkmcnt(6)
	v_mfma_f32_32x32x16_bf16 a[16:31], v[52:55], v[48:51], a[16:31]
	s_add_i32 s3, s3, 2
	s_cmp_lt_u32 s3, 30
	s_waitcnt vmcnt(11)
	ds_write_b128 v84, v[4:7] offset:0x8000
	v_mfma_f32_32x32x16_bf16 a[0:15], v[52:55], v[44:47], a[0:15]
	s_waitcnt vmcnt(10)
	ds_write_b128 v84, v[8:11] offset:0x9000
	s_waitcnt lgkmcnt(5)
	v_mfma_f32_32x32x16_bf16 a[32:47], v[90:93], v[40:43], a[32:47]
	s_waitcnt vmcnt(9)
	ds_write_b128 v84, v[12:15] offset:0xa000
	v_mfma_f32_32x32x16_bf16 a[48:63], v[90:93], v[86:89], a[48:63]
	s_waitcnt vmcnt(8)
	ds_write_b128 v84, v[16:19] offset:0xb000
	s_waitcnt lgkmcnt(6)
	v_mfma_f32_32x32x16_bf16 a[64:79], v[94:97], v[40:43], a[64:79]
	s_waitcnt vmcnt(7)
	ds_write_b128 v84, v[20:23] offset:0xc000
	v_mfma_f32_32x32x16_bf16 a[80:95], v[94:97], v[86:89], a[80:95]
	s_waitcnt vmcnt(6)
	ds_write_b128 v84, v[24:27] offset:0xd000
	s_waitcnt lgkmcnt(7)
	v_mfma_f32_32x32x16_bf16 a[96:111], v[98:101], v[40:43], a[96:111]
	v_lshl_add_u64 v[4:5], v[68:69], 0, s[78:79]
	v_lshl_add_u64 v[8:9], v[72:73], 0, s[6:7]
	v_lshl_add_u64 v[12:13], v[74:75], 0, s[6:7]
	v_mfma_f32_32x32x16_bf16 a[112:127], v[98:101], v[86:89], a[112:127]
	v_lshl_add_u64 v[16:17], v[76:77], 0, s[6:7]
	v_lshl_add_u64 v[20:21], v[70:71], 0, s[78:79]
	v_lshl_add_u64 v[24:25], v[78:79], 0, s[6:7]
	s_waitcnt lgkmcnt(0)
	s_barrier
	ds_read_b128 v[44:47], v82 offset:0x8000
	ds_read_b128 v[48:51], v82 offset:0x8800
	ds_read_b128 v[52:55], v80 offset:0x8000
	ds_read_b128 v[56:59], v80 offset:0x8800
	ds_read_b128 v[60:63], v80 offset:0x9000
	ds_read_b128 v[64:67], v80 offset:0x9800
	v_mfma_f32_32x32x16_bf16 a[16:31], v[102:105], v[40:43], a[16:31]
	v_mfma_f32_32x32x16_bf16 a[0:15], v[102:105], v[86:89], a[0:15]
	global_load_dwordx4 v[4:7], v[4:5], off offset:192
	s_waitcnt lgkmcnt(3)
	v_mfma_f32_32x32x16_bf16 a[32:47], v[52:55], v[44:47], a[32:47]
	ds_read_b128 v[40:43], v83 offset:0x8000
	global_load_dwordx4 v[8:11], v[8:9], off
	v_mfma_f32_32x32x16_bf16 a[48:63], v[52:55], v[48:51], a[48:63]
	ds_read_b128 v[128:131], v83 offset:0x8800
	global_load_dwordx4 v[12:15], v[12:13], off
	s_waitcnt lgkmcnt(4)
	v_mfma_f32_32x32x16_bf16 a[64:79], v[56:59], v[44:47], a[64:79]
	ds_read_b128 v[86:89], v81 offset:0x8000
	global_load_dwordx4 v[16:19], v[16:17], off
	v_mfma_f32_32x32x16_bf16 a[80:95], v[56:59], v[48:51], a[80:95]
	ds_read_b128 v[90:93], v81 offset:0x8800
	global_load_dwordx4 v[20:23], v[20:21], off offset:192
	s_waitcnt lgkmcnt(5)
	v_mfma_f32_32x32x16_bf16 a[96:111], v[60:63], v[44:47], a[96:111]
	ds_read_b128 v[94:97], v81 offset:0x9000
	global_load_dwordx4 v[24:27], v[24:25], off
	v_mfma_f32_32x32x16_bf16 a[112:127], v[60:63], v[48:51], a[112:127]
	ds_read_b128 v[132:135], v81 offset:0x9800
	s_waitcnt lgkmcnt(6)
	v_mfma_f32_32x32x16_bf16 a[16:31], v[64:67], v[44:47], a[16:31]
	s_waitcnt vmcnt(11)
	ds_write_b128 v84, v[106:109] offset:0
	v_mfma_f32_32x32x16_bf16 a[0:15], v[64:67], v[48:51], a[0:15]
	s_waitcnt vmcnt(10)
	ds_write_b128 v84, v[110:113] offset:0x1000
	s_waitcnt lgkmcnt(5)
	v_mfma_f32_32x32x16_bf16 a[32:47], v[86:89], v[40:43], a[32:47]
	s_waitcnt vmcnt(9)
	ds_write_b128 v84, v[114:117] offset:0x2000
	v_mfma_f32_32x32x16_bf16 a[48:63], v[86:89], v[128:131], a[48:63]
	s_waitcnt vmcnt(8)
	ds_write_b128 v84, v[118:121] offset:0x3000
	s_waitcnt lgkmcnt(6)
	v_mfma_f32_32x32x16_bf16 a[64:79], v[90:93], v[40:43], a[64:79]
	s_waitcnt vmcnt(7)
	ds_write_b128 v84, v[122:125] offset:0x4000
	v_mfma_f32_32x32x16_bf16 a[80:95], v[90:93], v[128:131], a[80:95]
	s_waitcnt vmcnt(6)
	ds_write_b128 v84, v[140:143] offset:0x5000
	s_waitcnt lgkmcnt(7)
	v_mfma_f32_32x32x16_bf16 a[96:111], v[94:97], v[40:43], a[96:111]
	v_mfma_f32_32x32x16_bf16 a[112:127], v[94:97], v[128:131], a[112:127]
	s_waitcnt lgkmcnt(0)
	s_barrier
	s_cbranch_scc0 .LBB0_222
	s_mov_b32 s4, s5
	s_branch .Lrs4_top

.LBB0_773:
.Lrs5_top:
	s_cmp_eq_u32 s3, 0
	ds_read_b128 v[44:47], v78 offset:0
	ds_read_b128 v[40:43], v78 offset:0x800
	ds_read_b128 v[60:63], v76 offset:0
	ds_read_b128 v[56:59], v76 offset:0x800
	ds_read_b128 v[52:55], v76 offset:0x1000
	ds_read_b128 v[48:51], v76 offset:0x1800
	s_cbranch_scc1 .Lrs5_skip
	v_mfma_f32_32x32x16_bf16 a[0:15], v[198:201], v[202:205], a[0:15]
	v_mfma_f32_32x32x16_bf16 a[128:143], v[198:201], v[194:197], a[128:143]
.Lrs5_skip:
	s_add_i32 s4, s3, 64
	s_min_u32 s5, s4, 0x3e0
	s_lshl_b32 s78, s5, 1
	v_lshl_add_u64 v[106:107], v[64:65], 0, s[78:79]
	global_load_dwordx4 v[106:109], v[106:107], off
	s_waitcnt lgkmcnt(3)
	v_mfma_f32_32x32x16_bf16 a[112:127], v[60:63], v[44:47], a[112:127]
	ds_read_b128 v[82:85], v79 offset:0
	v_lshl_add_u64 v[110:111], v[68:69], 0, s[78:79]
	global_load_dwordx4 v[110:113], v[110:111], off
	v_mfma_f32_32x32x16_bf16 a[96:111], v[60:63], v[40:43], a[96:111]
	ds_read_b128 v[86:89], v79 offset:0x800
	v_lshl_add_u64 v[114:115], v[70:71], 0, s[78:79]
	global_load_dwordx4 v[114:117], v[114:115], off
	s_waitcnt lgkmcnt(4)
	v_mfma_f32_32x32x16_bf16 a[80:95], v[56:59], v[44:47], a[80:95]
	ds_read_b128 v[90:93], v77 offset:0
	v_lshl_add_u64 v[118:119], v[72:73], 0, s[78:79]
	global_load_dwordx4 v[118:121], v[118:119], off
	v_mfma_f32_32x32x16_bf16 a[64:79], v[56:59], v[40:43], a[64:79]
	ds_read_b128 v[94:97], v77 offset:0x800
	v_lshl_add_u64 v[122:123], v[66:67], 0, s[78:79]
	global_load_dwordx4 v[122:125], v[122:123], off
	s_waitcnt lgkmcnt(5)
	v_mfma_f32_32x32x16_bf16 a[48:63], v[52:55], v[44:47], a[48:63]
	ds_read_b128 v[98:101], v77 offset:0x1000
	v_lshl_add_u64 v[126:127], v[74:75], 0, s[78:79]
	global_load_dwordx4 v[126:129], v[126:127], off
	s_min_u32 s3, s3, 0x380
	s_lshl_b32 s78, s3, 1
	v_mfma_f32_32x32x16_bf16 a[16:31], v[52:55], v[40:43], a[16:31]
	ds_read_b128 v[102:105], v77 offset:0x1800
	s_add_i32 s6, s78, 0xc0
	s_mov_b32 s7, s79
	s_waitcnt lgkmcnt(6)
	v_mfma_f32_32x32x16_bf16 a[0:15], v[48:51], v[44:47], a[0:15]
	s_add_i32 s2, s2, 2
	s_cmp_gt_u32 s2, 29
	s_waitcnt vmcnt(11)
	ds_write_b128 v80, v[4:7] offset:0x8000
	v_mfma_f32_32x32x16_bf16 a[128:143], v[48:51], v[40:43], a[128:143]
	s_waitcnt vmcnt(10)
	ds_write_b128 v80, v[8:11] offset:0x9000
	s_waitcnt lgkmcnt(5)
	v_mfma_f32_32x32x16_bf16 a[112:127], v[90:93], v[82:85], a[112:127]
	s_waitcnt vmcnt(9)
	ds_write_b128 v80, v[12:15] offset:0xa000
	v_mfma_f32_32x32x16_bf16 a[96:111], v[90:93], v[86:89], a[96:111]
	s_waitcnt vmcnt(8)
	ds_write_b128 v80, v[16:19] offset:0xb000
	s_waitcnt lgkmcnt(6)
	v_mfma_f32_32x32x16_bf16 a[80:95], v[94:97], v[82:85], a[80:95]
	s_waitcnt vmcnt(7)
	ds_write_b128 v80, v[20:23] offset:0xc000
	v_mfma_f32_32x32x16_bf16 a[64:79], v[94:97], v[86:89], a[64:79]
	s_waitcnt vmcnt(6)
	ds_write_b128 v80, v[24:27] offset:0xd000
	s_waitcnt lgkmcnt(7)
	v_mfma_f32_32x32x16_bf16 a[48:63], v[98:101], v[82:85], a[48:63]
	v_lshl_add_u64 v[4:5], v[64:65], 0, s[78:79]
	v_lshl_add_u64 v[8:9], v[68:69], 0, s[6:7]
	v_lshl_add_u64 v[12:13], v[70:71], 0, s[6:7]
	v_mfma_f32_32x32x16_bf16 a[16:31], v[98:101], v[86:89], a[16:31]
	v_lshl_add_u64 v[16:17], v[72:73], 0, s[6:7]
	v_lshl_add_u64 v[20:21], v[66:67], 0, s[78:79]
	v_lshl_add_u64 v[24:25], v[74:75], 0, s[6:7]
	s_waitcnt lgkmcnt(0)
	s_barrier
	ds_read_b128 v[40:43], v78 offset:0x8000
	ds_read_b128 v[44:47], v78 offset:0x8800
	ds_read_b128 v[48:51], v76 offset:0x8000
	ds_read_b128 v[52:55], v76 offset:0x8800
	ds_read_b128 v[56:59], v76 offset:0x9000
	ds_read_b128 v[60:63], v76 offset:0x9800
	v_mfma_f32_32x32x16_bf16 a[0:15], v[102:105], v[82:85], a[0:15]
	v_mfma_f32_32x32x16_bf16 a[128:143], v[102:105], v[86:89], a[128:143]
	global_load_dwordx4 v[4:7], v[4:5], off offset:192
	s_waitcnt lgkmcnt(3)
	v_mfma_f32_32x32x16_bf16 a[112:127], v[48:51], v[40:43], a[112:127]
	ds_read_b128 v[202:205], v79 offset:0x8000
	global_load_dwordx4 v[8:11], v[8:9], off
	v_mfma_f32_32x32x16_bf16 a[96:111], v[48:51], v[44:47], a[96:111]
	ds_read_b128 v[194:197], v79 offset:0x8800
	global_load_dwordx4 v[12:15], v[12:13], off
	s_waitcnt lgkmcnt(4)
	v_mfma_f32_32x32x16_bf16 a[80:95], v[52:55], v[40:43], a[80:95]
	ds_read_b128 v[82:85], v77 offset:0x8000
	global_load_dwordx4 v[16:19], v[16:17], off
	v_mfma_f32_32x32x16_bf16 a[64:79], v[52:55], v[44:47], a[64:79]
	ds_read_b128 v[86:89], v77 offset:0x8800
	global_load_dwordx4 v[20:23], v[20:21], off offset:192
	s_waitcnt lgkmcnt(5)
	v_mfma_f32_32x32x16_bf16 a[48:63], v[56:59], v[40:43], a[48:63]
	ds_read_b128 v[90:93], v77 offset:0x9000
	global_load_dwordx4 v[24:27], v[24:25], off
	v_mfma_f32_32x32x16_bf16 a[16:31], v[56:59], v[44:47], a[16:31]
	ds_read_b128 v[198:201], v77 offset:0x9800
	s_waitcnt lgkmcnt(6)
	v_mfma_f32_32x32x16_bf16 a[0:15], v[60:63], v[40:43], a[0:15]
	s_waitcnt vmcnt(11)
	ds_write_b128 v80, v[106:109] offset:0
	v_mfma_f32_32x32x16_bf16 a[128:143], v[60:63], v[44:47], a[128:143]
	s_waitcnt vmcnt(10)
	ds_write_b128 v80, v[110:113] offset:0x1000
	s_waitcnt lgkmcnt(5)
	v_mfma_f32_32x32x16_bf16 a[112:127], v[82:85], v[202:205], a[112:127]
	s_waitcnt vmcnt(9)
	ds_write_b128 v80, v[114:117] offset:0x2000
	v_mfma_f32_32x32x16_bf16 a[96:111], v[82:85], v[194:197], a[96:111]
	s_waitcnt vmcnt(8)
	ds_write_b128 v80, v[118:121] offset:0x3000
	s_waitcnt lgkmcnt(6)
	v_mfma_f32_32x32x16_bf16 a[80:95], v[86:89], v[202:205], a[80:95]
	s_waitcnt vmcnt(7)
	ds_write_b128 v80, v[122:125] offset:0x4000
	v_mfma_f32_32x32x16_bf16 a[64:79], v[86:89], v[194:197], a[64:79]
	s_waitcnt vmcnt(6)
	ds_write_b128 v80, v[126:129] offset:0x5000
	s_waitcnt lgkmcnt(7)
	v_mfma_f32_32x32x16_bf16 a[48:63], v[90:93], v[202:205], a[48:63]
	v_mfma_f32_32x32x16_bf16 a[16:31], v[90:93], v[194:197], a[16:31]
	s_waitcnt lgkmcnt(0)
	s_barrier
	s_cbranch_scc1 .LBB0_777
	s_mov_b32 s3, s4
	s_branch .Lrs5_top
